# baseline (speedup 1.0000x reference)
; template <int NT, int BM, int BN, bool PLAIN, int NSTAGE, bool EPI_LDS>
; __device__ __forceinline__ void gemm_tile(const Params& p, const GemmDesc& g, bf16_t* lds, const int tid) {
;     ...
;       for (; kt + 2 < nk; ++kt) {
;         const int cur = kt & 1;
;         COMPUTE_X(cur, 1, 1, kt + 2)
;         __syncthreads();
;       }
.LBB0_897:
	s_waitcnt lgkmcnt(2)
	v_mfma_f32_16x16x32_bf16 v[158:161], v[2:5], v[202:205], v[158:161]
	global_load_lds_dwordx4 v166, s[60:61]
	s_add_u32 m0, m0, 0x400
	v_add_u32_e32 v218, v218, v181
	s_add_i32 s27, s27, -1
	v_mfma_f32_16x16x32_bf16 v[154:157], v[6:9], v[202:205], v[154:157]
	s_add_i32 s26, s26, 0x10000
	v_mfma_f32_16x16x32_bf16 v[150:153], v[10:13], v[202:205], v[150:153]
	global_load_lds_dwordx4 v167, s[60:61]
	s_add_u32 m0, m0, 0x400
	v_mfma_f32_16x16x32_bf16 v[146:149], v[14:17], v[202:205], v[146:149]
	ds_read_b128 v[202:205], v0 offset:6144
	s_waitcnt lgkmcnt(2)
	v_mfma_f32_16x16x32_bf16 v[142:145], v[2:5], v[206:209], v[142:145]
	global_load_lds_dwordx4 v168, s[60:61]
	s_add_u32 m0, m0, 0x400
	v_mfma_f32_16x16x32_bf16 v[138:141], v[6:9], v[206:209], v[138:141]
	v_mfma_f32_16x16x32_bf16 v[134:137], v[10:13], v[206:209], v[134:137]
	global_load_lds_dwordx4 v169, s[60:61]
	s_add_u32 s60, s60, 0x80
	s_addc_u32 s61, s61, 0
	v_mfma_f32_16x16x32_bf16 v[130:133], v[14:17], v[206:209], v[130:133]
	ds_read_b128 v[206:209], v0 offset:8192
	s_waitcnt lgkmcnt(2)
	v_mfma_f32_16x16x32_bf16 v[126:129], v[2:5], v[226:229], v[126:129]
	v_mfma_f32_16x16x32_bf16 v[122:125], v[6:9], v[226:229], v[122:125]
	v_mfma_f32_16x16x32_bf16 v[118:121], v[10:13], v[226:229], v[118:121]
	v_mfma_f32_16x16x32_bf16 v[114:117], v[14:17], v[226:229], v[114:117]
	ds_read_b128 v[226:229], v0 offset:10240
	s_waitcnt lgkmcnt(2)
	v_mfma_f32_16x16x32_bf16 v[106:109], v[2:5], v[202:205], v[106:109]
	v_mfma_f32_16x16x32_bf16 v[102:105], v[6:9], v[202:205], v[102:105]
	v_mfma_f32_16x16x32_bf16 v[98:101], v[10:13], v[202:205], v[98:101]
	v_mfma_f32_16x16x32_bf16 v[94:97], v[14:17], v[202:205], v[94:97]
	ds_read_b128 v[202:205], v0 offset:12288
	ds_read_b128 v[230:233], v218 offset:32768
	s_waitcnt lgkmcnt(3)
	v_mfma_f32_16x16x32_bf16 v[86:89], v[2:5], v[206:209], v[86:89]
	v_mfma_f32_16x16x32_bf16 v[82:85], v[6:9], v[206:209], v[82:85]
	v_mfma_f32_16x16x32_bf16 v[78:81], v[10:13], v[206:209], v[78:81]
	v_mfma_f32_16x16x32_bf16 v[74:77], v[14:17], v[206:209], v[74:77]
	ds_read_b128 v[206:209], v0 offset:14336
	ds_read_b128 v[234:237], v218 offset:34816
	v_add_u32_e32 v0, v0, v181
	s_waitcnt lgkmcnt(4)
	v_mfma_f32_16x16x32_bf16 v[70:73], v[2:5], v[226:229], v[70:73]
	v_mfma_f32_16x16x32_bf16 v[66:69], v[6:9], v[226:229], v[66:69]
	v_mfma_f32_16x16x32_bf16 v[62:65], v[10:13], v[226:229], v[62:65]
	v_mfma_f32_16x16x32_bf16 v[58:61], v[14:17], v[226:229], v[58:61]
	ds_read_b128 v[226:229], v0 offset:0
	ds_read_b128 v[238:241], v218 offset:36864
	s_waitcnt lgkmcnt(5)
	v_mfma_f32_16x16x32_bf16 v[54:57], v[2:5], v[202:205], v[54:57]
	v_mfma_f32_16x16x32_bf16 v[50:53], v[6:9], v[202:205], v[50:53]
	v_mfma_f32_16x16x32_bf16 v[46:49], v[10:13], v[202:205], v[46:49]
	v_mfma_f32_16x16x32_bf16 v[42:45], v[14:17], v[202:205], v[42:45]
	ds_read_b128 v[202:205], v0 offset:2048
	ds_read_b128 v[242:245], v218 offset:38912
	s_waitcnt lgkmcnt(5)
	v_mfma_f32_16x16x32_bf16 v[38:41], v[2:5], v[206:209], v[38:41]
	v_mfma_f32_16x16x32_bf16 v[34:37], v[6:9], v[206:209], v[34:37]
	v_mfma_f32_16x16x32_bf16 v[90:93], v[10:13], v[206:209], v[90:93]
	v_mfma_f32_16x16x32_bf16 v[110:113], v[14:17], v[206:209], v[110:113]
	ds_read_b128 v[186:189], v0 offset:4096
	s_waitcnt lgkmcnt(4)
	v_mfma_f32_16x16x32_bf16 v[158:161], v[230:233], v[226:229], v[158:161]
	v_mfma_f32_16x16x32_bf16 v[154:157], v[234:237], v[226:229], v[154:157]
	s_waitcnt lgkmcnt(3)
	v_mfma_f32_16x16x32_bf16 v[150:153], v[238:241], v[226:229], v[150:153]
	s_waitcnt lgkmcnt(1)
	v_mfma_f32_16x16x32_bf16 v[146:149], v[242:245], v[226:229], v[146:149]
	ds_read_b128 v[190:193], v0 offset:6144
	v_mfma_f32_16x16x32_bf16 v[142:145], v[230:233], v[202:205], v[142:145]
	v_mfma_f32_16x16x32_bf16 v[138:141], v[234:237], v[202:205], v[138:141]
	v_mfma_f32_16x16x32_bf16 v[134:137], v[238:241], v[202:205], v[134:137]
	v_mfma_f32_16x16x32_bf16 v[130:133], v[242:245], v[202:205], v[130:133]
	ds_read_b128 v[194:197], v0 offset:8192
	s_waitcnt lgkmcnt(2)
	v_mfma_f32_16x16x32_bf16 v[126:129], v[230:233], v[186:189], v[126:129]
	v_mfma_f32_16x16x32_bf16 v[122:125], v[234:237], v[186:189], v[122:125]
	v_mfma_f32_16x16x32_bf16 v[118:121], v[238:241], v[186:189], v[118:121]
	v_mfma_f32_16x16x32_bf16 v[114:117], v[242:245], v[186:189], v[114:117]
	ds_read_b128 v[186:189], v0 offset:10240
	s_waitcnt lgkmcnt(2)
	v_mfma_f32_16x16x32_bf16 v[106:109], v[230:233], v[190:193], v[106:109]
	v_mfma_f32_16x16x32_bf16 v[102:105], v[234:237], v[190:193], v[102:105]
	v_mfma_f32_16x16x32_bf16 v[98:101], v[238:241], v[190:193], v[98:101]
	v_mfma_f32_16x16x32_bf16 v[94:97], v[242:245], v[190:193], v[94:97]
	ds_read_b128 v[190:193], v0 offset:12288
	s_waitcnt lgkmcnt(2)
	v_mfma_f32_16x16x32_bf16 v[86:89], v[230:233], v[194:197], v[86:89]
	v_mfma_f32_16x16x32_bf16 v[82:85], v[234:237], v[194:197], v[82:85]
	v_mfma_f32_16x16x32_bf16 v[78:81], v[238:241], v[194:197], v[78:81]
	v_mfma_f32_16x16x32_bf16 v[74:77], v[242:245], v[194:197], v[74:77]
	ds_read_b128 v[194:197], v0 offset:14336
	s_waitcnt lgkmcnt(2)
	v_mfma_f32_16x16x32_bf16 v[70:73], v[230:233], v[186:189], v[70:73]
	v_mfma_f32_16x16x32_bf16 v[66:69], v[234:237], v[186:189], v[66:69]
	v_mfma_f32_16x16x32_bf16 v[62:65], v[238:241], v[186:189], v[62:65]
	v_mfma_f32_16x16x32_bf16 v[58:61], v[242:245], v[186:189], v[58:61]
	s_xor_b32 s29, s28, 0x10000
	v_or_b32_e32 v18, s29, v180
	v_add_u32_e32 v19, v18, v184
	v_add_u32_e32 v18, v18, v183
	s_waitcnt vmcnt(0) lgkmcnt(0)
	s_barrier
; template <int NT, int BM, int BN, bool PLAIN, int NSTAGE, bool EPI_LDS>
; __device__ __forceinline__ void gemm_tile(const Params& p, const GemmDesc& g, bf16_t* lds, const int tid) {
;     ...
;     if (PLAIN) {
;       int kt = 0;
;       for (; kt + 2 < nk; ++kt) {
;         const int cur = kt & 1;
;         COMPUTE_X(cur, 1, 1, kt + 2)
;         __syncthreads();
;       }
;       if (kt + 1 < nk) {
;         const int cur = kt & 1;
;         COMPUTE_X(cur, 1, 0, 0)
;         __syncthreads();
;         ++kt;
	ds_read_b128 v[2:5], v19 offset:32768
	ds_read_b128 v[6:9], v19 offset:34816
	ds_read_b128 v[10:13], v19 offset:36864
	ds_read_b128 v[14:17], v19 offset:38912
	ds_read_b128 v[202:205], v18
	ds_read_b128 v[206:209], v18 offset:2048
	ds_read_b128 v[226:229], v18 offset:4096
	s_add_u32 m0, s28, s57
	v_mfma_f32_16x16x32_bf16 v[54:57], v[230:233], v[190:193], v[54:57]
	global_load_lds_dwordx4 v162, s[60:61]
	s_add_u32 m0, m0, 0x400
	v_mfma_f32_16x16x32_bf16 v[50:53], v[234:237], v[190:193], v[50:53]
	v_mfma_f32_16x16x32_bf16 v[46:49], v[238:241], v[190:193], v[46:49]
	global_load_lds_dwordx4 v163, s[60:61]
	s_add_u32 m0, m0, 0x400
	v_mfma_f32_16x16x32_bf16 v[42:45], v[242:245], v[190:193], v[42:45]
	v_mfma_f32_16x16x32_bf16 v[38:41], v[230:233], v[194:197], v[38:41]
	global_load_lds_dwordx4 v164, s[60:61]
	s_add_u32 m0, m0, 0x400
	v_mfma_f32_16x16x32_bf16 v[34:37], v[234:237], v[194:197], v[34:37]
	v_mfma_f32_16x16x32_bf16 v[90:93], v[238:241], v[194:197], v[90:93]
	global_load_lds_dwordx4 v165, s[60:61]
	v_mfma_f32_16x16x32_bf16 v[110:113], v[242:245], v[194:197], v[110:113]
	s_and_b32 s28, s26, 0x10000
	s_xor_b32 s29, s28, 0x10000
	s_add_u32 m0, s29, s57
	s_add_u32 m0, m0, 0x1000
	v_or_b32_e32 v0, s28, v180
	v_add_u32_e32 v218, v0, v184
	v_add_u32_e32 v0, v0, v183
	s_cmp_lg_u32 s27, 0
	s_cbranch_scc1 .LBB0_897
	s_setprio 0
	s_lshl_b32 s3, s3, 16
	s_and_b32 s3, s3, 0x10000
	s_xor_b32 s29, s3, 0x10000
	s_add_u32 m0, s29, s57
	s_add_u32 m0, m0, 0x1000
	s_nop 0
	global_load_lds_dwordx4 v166, s[60:61]
	s_add_u32 m0, m0, 0x400
	s_nop 0
	global_load_lds_dwordx4 v167, s[60:61]
	s_add_u32 m0, m0, 0x400
	s_nop 0
	global_load_lds_dwordx4 v168, s[60:61]
	s_add_u32 m0, m0, 0x400
	s_nop 0
	global_load_lds_dwordx4 v169, s[60:61]
	v_or_b32_e32 v0, s3, v180
	v_add_u32_e32 v198, v0, v184
	ds_read_b128 v[162:165], v198 offset:32768
	ds_read_b128 v[166:169], v198 offset:34816
	ds_read_b128 v[170:173], v198 offset:36864
	ds_read_b128 v[186:189], v198 offset:38912
	v_add_u32_e32 v0, v0, v183
	ds_read_b128 v[174:177], v0
	ds_read_b128 v[190:193], v0 offset:2048
	ds_read_b128 v[194:197], v0 offset:4096
	s_waitcnt lgkmcnt(2)
	v_mfma_f32_16x16x32_bf16 v[30:33], v[162:165], v[174:177], v[158:161]
	s_not_b32 s3, s23
	s_lshl_b32 s3, s3, 16
	s_and_b32 s3, s3, 0x10000
	v_mfma_f32_16x16x32_bf16 v[154:157], v[166:169], v[174:177], v[154:157]
	s_cmp_lg_u32 s56, 9
	s_cselect_b64 s[26:27], -1, 0
	s_mov_b32 s24, s41
	v_mfma_f32_16x16x32_bf16 v[150:153], v[170:173], v[174:177], v[150:153]
	s_mov_b32 s23, s42
	s_mov_b64 s[28:29], -1
	s_and_b64 vcc, exec, s[26:27]
	v_mfma_f32_16x16x32_bf16 v[146:149], v[186:189], v[174:177], v[146:149]
	ds_read_b128 v[158:161], v0 offset:6144
	v_add_u32_e32 v174, v198, v181
	s_waitcnt lgkmcnt(2)
	v_mfma_f32_16x16x32_bf16 v[26:29], v[162:165], v[190:193], v[142:145]
	v_mfma_f32_16x16x32_bf16 v[138:141], v[166:169], v[190:193], v[138:141]
	v_mfma_f32_16x16x32_bf16 v[134:137], v[170:173], v[190:193], v[134:137]
	v_mfma_f32_16x16x32_bf16 v[130:133], v[186:189], v[190:193], v[130:133]
	ds_read_b128 v[142:145], v0 offset:8192
	s_waitcnt lgkmcnt(2)
	v_mfma_f32_16x16x32_bf16 v[22:25], v[162:165], v[194:197], v[126:129]
	v_mfma_f32_16x16x32_bf16 v[122:125], v[166:169], v[194:197], v[122:125]
	v_mfma_f32_16x16x32_bf16 v[118:121], v[170:173], v[194:197], v[118:121]
	v_mfma_f32_16x16x32_bf16 v[114:117], v[186:189], v[194:197], v[114:117]
	ds_read_b128 v[126:129], v0 offset:10240
	s_waitcnt lgkmcnt(2)
	v_mfma_f32_16x16x32_bf16 v[18:21], v[162:165], v[158:161], v[106:109]
	v_mfma_f32_16x16x32_bf16 v[102:105], v[166:169], v[158:161], v[102:105]
	v_mfma_f32_16x16x32_bf16 v[98:101], v[170:173], v[158:161], v[98:101]
	v_mfma_f32_16x16x32_bf16 v[94:97], v[186:189], v[158:161], v[94:97]
	ds_read_b128 v[106:109], v0 offset:12288
	ds_read_b128 v[158:161], v174 offset:32768
	s_waitcnt lgkmcnt(3)
	v_mfma_f32_16x16x32_bf16 v[14:17], v[162:165], v[142:145], v[86:89]
	v_mfma_f32_16x16x32_bf16 v[82:85], v[166:169], v[142:145], v[82:85]
	v_mfma_f32_16x16x32_bf16 v[78:81], v[170:173], v[142:145], v[78:81]
	v_mfma_f32_16x16x32_bf16 v[74:77], v[186:189], v[142:145], v[74:77]
	ds_read_b128 v[86:89], v0 offset:14336
	ds_read_b128 v[142:145], v174 offset:34816
	v_add_u32_e32 v0, v0, v181
	s_waitcnt lgkmcnt(4)
	v_mfma_f32_16x16x32_bf16 v[10:13], v[162:165], v[126:129], v[70:73]
	v_mfma_f32_16x16x32_bf16 v[66:69], v[166:169], v[126:129], v[66:69]
	v_mfma_f32_16x16x32_bf16 v[62:65], v[170:173], v[126:129], v[62:65]
	v_mfma_f32_16x16x32_bf16 v[58:61], v[186:189], v[126:129], v[58:61]
	ds_read_b128 v[70:73], v0 offset:0
	ds_read_b128 v[126:129], v174 offset:36864
	s_waitcnt lgkmcnt(5)
	v_mfma_f32_16x16x32_bf16 v[6:9], v[162:165], v[106:109], v[54:57]
	v_mfma_f32_16x16x32_bf16 v[50:53], v[166:169], v[106:109], v[50:53]
	v_mfma_f32_16x16x32_bf16 v[46:49], v[170:173], v[106:109], v[46:49]
	v_mfma_f32_16x16x32_bf16 v[42:45], v[186:189], v[106:109], v[42:45]
	ds_read_b128 v[106:109], v174 offset:38912
	ds_read_b128 v[54:57], v0 offset:2048
	s_waitcnt lgkmcnt(5)
	v_mfma_f32_16x16x32_bf16 v[2:5], v[162:165], v[86:89], v[38:41]
	v_mfma_f32_16x16x32_bf16 v[34:37], v[166:169], v[86:89], v[34:37]
	v_mfma_f32_16x16x32_bf16 v[38:41], v[170:173], v[86:89], v[90:93]
	v_mfma_f32_16x16x32_bf16 v[86:89], v[186:189], v[86:89], v[110:113]
	s_nop 1
	ds_read_b128 v[90:93], v0 offset:4096
	s_waitcnt lgkmcnt(4)
	v_mfma_f32_16x16x32_bf16 v[30:33], v[158:161], v[70:73], v[30:33]
	v_mfma_f32_16x16x32_bf16 v[110:113], v[142:145], v[70:73], v[154:157]
	s_waitcnt lgkmcnt(3)
	v_mfma_f32_16x16x32_bf16 v[150:153], v[126:129], v[70:73], v[150:153]
	s_waitcnt lgkmcnt(2)
; template <int NT, int BM, int BN, bool PLAIN, int NSTAGE, bool EPI_LDS>
; __device__ __forceinline__ void gemm_tile(const Params& p, const GemmDesc& g, bf16_t* lds, const int tid) {
;     ...
;       if (kt + 1 < nk) {
;         const int cur = kt & 1;
;         COMPUTE_X(cur, 1, 0, 0)
;         __syncthreads();
;         ++kt;
;       }
	v_mfma_f32_16x16x32_bf16 v[70:73], v[106:109], v[70:73], v[146:149]
	s_nop 2
	ds_read_b128 v[146:149], v0 offset:6144
	s_waitcnt lgkmcnt(2)
	v_mfma_f32_16x16x32_bf16 v[26:29], v[158:161], v[54:57], v[26:29]
	v_mfma_f32_16x16x32_bf16 v[138:141], v[142:145], v[54:57], v[138:141]
	v_mfma_f32_16x16x32_bf16 v[134:137], v[126:129], v[54:57], v[134:137]
	v_mfma_f32_16x16x32_bf16 v[54:57], v[106:109], v[54:57], v[130:133]
	s_nop 2
	ds_read_b128 v[130:133], v0 offset:8192
	s_waitcnt lgkmcnt(2)
	v_mfma_f32_16x16x32_bf16 v[22:25], v[158:161], v[90:93], v[22:25]
	v_mfma_f32_16x16x32_bf16 v[122:125], v[142:145], v[90:93], v[122:125]
	v_mfma_f32_16x16x32_bf16 v[118:121], v[126:129], v[90:93], v[118:121]
	v_mfma_f32_16x16x32_bf16 v[90:93], v[106:109], v[90:93], v[114:117]
	s_nop 2
	ds_read_b128 v[114:117], v0 offset:10240
	s_waitcnt lgkmcnt(2)
	v_mfma_f32_16x16x32_bf16 v[18:21], v[158:161], v[146:149], v[18:21]
	v_mfma_f32_16x16x32_bf16 v[102:105], v[142:145], v[146:149], v[102:105]
	v_mfma_f32_16x16x32_bf16 v[98:101], v[126:129], v[146:149], v[98:101]
	v_mfma_f32_16x16x32_bf16 v[94:97], v[106:109], v[146:149], v[94:97]
	ds_read_b128 v[146:149], v0 offset:12288
	s_waitcnt lgkmcnt(2)
	v_mfma_f32_16x16x32_bf16 v[14:17], v[158:161], v[130:133], v[14:17]
	v_mfma_f32_16x16x32_bf16 v[82:85], v[142:145], v[130:133], v[82:85]
	v_mfma_f32_16x16x32_bf16 v[78:81], v[126:129], v[130:133], v[78:81]
	v_mfma_f32_16x16x32_bf16 v[74:77], v[106:109], v[130:133], v[74:77]
	ds_read_b128 v[130:133], v0 offset:14336
	v_or_b32_e32 v0, s3, v180
	v_add_u32_e32 v186, v0, v184
	s_waitcnt lgkmcnt(2)
	v_mfma_f32_16x16x32_bf16 v[10:13], v[158:161], v[114:117], v[10:13]
	s_waitcnt vmcnt(0) lgkmcnt(0)
	s_barrier
; template <int NT, int BM, int BN, bool PLAIN, int NSTAGE, bool EPI_LDS>
; __device__ __forceinline__ void gemm_tile(const Params& p, const GemmDesc& g, bf16_t* lds, const int tid) {
;     ...
;       {
;         const int cur = kt & 1;
;         COMPUTE_X(cur, 0, 0, 0)
;         __syncthreads();
;       }
;     } else {
;       for (int kt = 0; kt < nk; ++kt) {
;         const int cur = kt & 1;
;         if (kt + 1 < nk) {
;           LWRITE(cur ^ 1)
;           if (kt + 2 < nk) GLOAD(kt + 2)
;         }
;         __builtin_amdgcn_sched_barrier(0);
;         COMPUTE(cur)
;         __syncthreads();
;       }
;     }
;   }
;     ...
;   int m0e = m0, n0e = n0;
;   asm volatile("" : "+s"(m0e), "+s"(n0e));
;   if (EPI_LDS) {
;     constexpr int CST = BN + 16;
;     bf16_t* ct = lds;
;     const bool relu2 = (g.epi == E_RELU2);
; #pragma unroll
;     for (int mi = 0; mi < MI; ++mi)
; #pragma unroll
;       for (int ni = 0; ni < NI; ++ni) {
;         f32x4 v = acc[mi][ni];
;         if (relu2) {
; #pragma unroll
;           for (int j = 0; j < 4; ++j) { const float r = fmaxf(v[j], 0.f); v[j] = r * r; }
;         }
;         u32x2 w;
;         w[0] = pack2(v[0], v[1]);
;         w[1] = pack2(v[2], v[3]);
;         *(u32x2*)(ct + (wm * WTM + mi * 16 + fr) * CST + wn * WTN + ni * 16 + fq * 4) = w;
	v_mfma_f32_16x16x32_bf16 v[66:69], v[142:145], v[114:117], v[66:69]
	v_add_u32_e32 v0, v0, v183
	v_mfma_f32_16x16x32_bf16 v[62:65], v[126:129], v[114:117], v[62:65]
	v_mfma_f32_16x16x32_bf16 v[58:61], v[106:109], v[114:117], v[58:61]
	v_mfma_f32_16x16x32_bf16 v[6:9], v[158:161], v[146:149], v[6:9]
	v_mfma_f32_16x16x32_bf16 v[50:53], v[142:145], v[146:149], v[50:53]
	v_mfma_f32_16x16x32_bf16 v[46:49], v[126:129], v[146:149], v[46:49]
	v_mfma_f32_16x16x32_bf16 v[42:45], v[106:109], v[146:149], v[42:45]
	v_mfma_f32_16x16x32_bf16 v[2:5], v[158:161], v[130:133], v[2:5]
	v_mfma_f32_16x16x32_bf16 v[34:37], v[142:145], v[130:133], v[34:37]
	v_mfma_f32_16x16x32_bf16 v[38:41], v[126:129], v[130:133], v[38:41]
	v_mfma_f32_16x16x32_bf16 v[86:89], v[106:109], v[130:133], v[86:89]
	ds_read_b128 v[106:109], v186 offset:32768
	ds_read_b128 v[114:117], v186 offset:34816
	ds_read_b128 v[130:133], v186 offset:36864
	ds_read_b128 v[142:145], v186 offset:38912
	ds_read_b128 v[126:129], v0
	ds_read_b128 v[146:149], v0 offset:2048
	ds_read_b128 v[154:157], v0 offset:4096
	s_waitcnt lgkmcnt(2)
	v_mfma_f32_16x16x32_bf16 v[30:33], v[106:109], v[126:129], v[30:33]
	v_mfma_f32_16x16x32_bf16 v[110:113], v[114:117], v[126:129], v[110:113]
	v_mfma_f32_16x16x32_bf16 v[150:153], v[130:133], v[126:129], v[150:153]
	v_mfma_f32_16x16x32_bf16 v[70:73], v[142:145], v[126:129], v[70:73]
	ds_read_b128 v[126:129], v0 offset:6144
	s_waitcnt lgkmcnt(2)
	v_mfma_f32_16x16x32_bf16 v[26:29], v[106:109], v[146:149], v[26:29]
	v_mfma_f32_16x16x32_bf16 v[138:141], v[114:117], v[146:149], v[138:141]
	v_mfma_f32_16x16x32_bf16 v[134:137], v[130:133], v[146:149], v[134:137]
	v_mfma_f32_16x16x32_bf16 v[54:57], v[142:145], v[146:149], v[54:57]
	ds_read_b128 v[146:149], v0 offset:8192
	s_waitcnt lgkmcnt(2)
	v_mfma_f32_16x16x32_bf16 v[22:25], v[106:109], v[154:157], v[22:25]
	v_mfma_f32_16x16x32_bf16 v[158:161], v[114:117], v[154:157], v[122:125]
	v_mfma_f32_16x16x32_bf16 v[162:165], v[130:133], v[154:157], v[118:121]
	v_mfma_f32_16x16x32_bf16 v[154:157], v[142:145], v[154:157], v[90:93]
	s_nop 2
	ds_read_b128 v[90:93], v0 offset:10240
	s_waitcnt lgkmcnt(2)
	v_mfma_f32_16x16x32_bf16 v[18:21], v[106:109], v[126:129], v[18:21]
	v_mfma_f32_16x16x32_bf16 v[166:169], v[114:117], v[126:129], v[102:105]
	v_mfma_f32_16x16x32_bf16 v[170:173], v[130:133], v[126:129], v[98:101]
	v_mfma_f32_16x16x32_bf16 v[174:177], v[142:145], v[126:129], v[94:97]
	s_nop 1
	v_add_u32_e32 v98, v186, v181
	ds_read_b128 v[186:189], v98 offset:32768
	ds_read_b128 v[94:97], v0 offset:12288
	s_waitcnt lgkmcnt(3)
	v_mfma_f32_16x16x32_bf16 v[14:17], v[106:109], v[146:149], v[14:17]
	v_mfma_f32_16x16x32_bf16 v[190:193], v[114:117], v[146:149], v[82:85]
	v_mfma_f32_16x16x32_bf16 v[194:197], v[130:133], v[146:149], v[78:81]
	v_mfma_f32_16x16x32_bf16 v[146:149], v[142:145], v[146:149], v[74:77]
	ds_read_b128 v[198:201], v98 offset:34816
	s_nop 1
	ds_read_b128 v[74:77], v0 offset:14336
	v_add_u32_e32 v0, v0, v181
	s_waitcnt lgkmcnt(4)
	v_mfma_f32_16x16x32_bf16 v[10:13], v[106:109], v[90:93], v[10:13]
	v_mfma_f32_16x16x32_bf16 v[202:205], v[114:117], v[90:93], v[66:69]
	v_mfma_f32_16x16x32_bf16 v[206:209], v[130:133], v[90:93], v[62:65]
	v_mfma_f32_16x16x32_bf16 v[226:229], v[142:145], v[90:93], v[58:61]
	ds_read_b128 v[230:233], v98 offset:36864
	s_nop 1
	ds_read_b128 v[58:61], v0 offset:0
	s_waitcnt lgkmcnt(4)
	v_mfma_f32_16x16x32_bf16 v[6:9], v[106:109], v[94:97], v[6:9]
	v_mfma_f32_16x16x32_bf16 v[234:237], v[114:117], v[94:97], v[50:53]
	v_mfma_f32_16x16x32_bf16 v[238:241], v[130:133], v[94:97], v[46:49]
	v_mfma_f32_16x16x32_bf16 v[242:245], v[142:145], v[94:97], v[42:45]
	ds_read_b128 v[246:249], v98 offset:38912
	s_nop 1
	ds_read_b128 v[42:45], v0 offset:2048
	s_waitcnt lgkmcnt(4)
	v_mfma_f32_16x16x32_bf16 v[2:5], v[106:109], v[74:77], v[2:5]
	v_mfma_f32_16x16x32_bf16 v[218:221], v[114:117], v[74:77], v[34:37]
	v_mfma_f32_16x16x32_bf16 v[130:133], v[130:133], v[74:77], v[38:41]
	v_mfma_f32_16x16x32_bf16 v[142:145], v[142:145], v[74:77], v[86:89]
	s_nop 0
	ds_read_b128 v[34:37], v0 offset:4096
	s_waitcnt lgkmcnt(3)
	v_mfma_f32_16x16x32_bf16 v[126:129], v[186:189], v[58:61], v[30:33]
	v_mfma_f32_16x16x32_bf16 v[122:125], v[198:201], v[58:61], v[110:113]
	v_mfma_f32_16x16x32_bf16 v[118:121], v[230:233], v[58:61], v[150:153]
	s_waitcnt lgkmcnt(2)
	v_mfma_f32_16x16x32_bf16 v[114:117], v[246:249], v[58:61], v[70:73]
	ds_read_b128 v[30:33], v0 offset:6144
	s_waitcnt lgkmcnt(2)
	v_mfma_f32_16x16x32_bf16 v[110:113], v[186:189], v[42:45], v[26:29]
	v_mfma_f32_16x16x32_bf16 v[106:109], v[198:201], v[42:45], v[138:141]
	v_mfma_f32_16x16x32_bf16 v[102:105], v[230:233], v[42:45], v[134:137]
	v_mfma_f32_16x16x32_bf16 v[98:101], v[246:249], v[42:45], v[54:57]
	ds_read_b128 v[26:29], v0 offset:8192
	s_waitcnt lgkmcnt(2)
	v_mfma_f32_16x16x32_bf16 v[94:97], v[186:189], v[34:37], v[22:25]
	v_mfma_f32_16x16x32_bf16 v[90:93], v[198:201], v[34:37], v[158:161]
	v_mfma_f32_16x16x32_bf16 v[86:89], v[230:233], v[34:37], v[162:165]
	v_mfma_f32_16x16x32_bf16 v[82:85], v[246:249], v[34:37], v[154:157]
	ds_read_b128 v[22:25], v0 offset:10240
	s_waitcnt lgkmcnt(2)
	v_mfma_f32_16x16x32_bf16 v[78:81], v[186:189], v[30:33], v[18:21]
	v_mfma_f32_16x16x32_bf16 v[74:77], v[198:201], v[30:33], v[166:169]
	v_mfma_f32_16x16x32_bf16 v[70:73], v[230:233], v[30:33], v[170:173]
	v_mfma_f32_16x16x32_bf16 v[66:69], v[246:249], v[30:33], v[174:177]
	ds_read_b128 v[18:21], v0 offset:12288
	s_waitcnt lgkmcnt(2)
	v_mfma_f32_16x16x32_bf16 v[62:65], v[186:189], v[26:29], v[14:17]
	v_mfma_f32_16x16x32_bf16 v[58:61], v[198:201], v[26:29], v[190:193]
	v_mfma_f32_16x16x32_bf16 v[54:57], v[230:233], v[26:29], v[194:197]
	v_mfma_f32_16x16x32_bf16 v[50:53], v[246:249], v[26:29], v[146:149]
	ds_read_b128 v[134:137], v0 offset:14336
	s_waitcnt lgkmcnt(0)
	s_barrier
	v_mfma_f32_16x16x32_bf16 v[46:49], v[186:189], v[22:25], v[10:13]
	v_mfma_f32_16x16x32_bf16 v[42:45], v[198:201], v[22:25], v[202:205]
	v_mfma_f32_16x16x32_bf16 v[38:41], v[230:233], v[22:25], v[206:209]
	v_mfma_f32_16x16x32_bf16 v[34:37], v[246:249], v[22:25], v[226:229]
	v_mfma_f32_16x16x32_bf16 v[30:33], v[186:189], v[18:21], v[6:9]
	v_mfma_f32_16x16x32_bf16 v[26:29], v[198:201], v[18:21], v[234:237]
	v_mfma_f32_16x16x32_bf16 v[22:25], v[230:233], v[18:21], v[238:241]
	v_mfma_f32_16x16x32_bf16 v[18:21], v[246:249], v[18:21], v[242:245]
	v_mfma_f32_16x16x32_bf16 v[14:17], v[186:189], v[134:137], v[2:5]
	v_mfma_f32_16x16x32_bf16 v[10:13], v[198:201], v[134:137], v[218:221]
	v_mfma_f32_16x16x32_bf16 v[2:5], v[230:233], v[134:137], v[130:133]
	v_mfma_f32_16x16x32_bf16 v[6:9], v[246:249], v[134:137], v[142:145]
	s_cbranch_vccz .LBB0_900
	s_nop 0
	v_cvt_pk_bf16_f32 v130, v126, v127
	v_cvt_pk_bf16_f32 v131, v128, v129
	s_mov_b64 s[28:29], 0
